# priority raise for waves 4-7 only during the attention units (RG-LRU at equal priority), rmsnorm raise kept
# speedup vs baseline: 1.0047x; 1.0047x over previous
; __device__ __forceinline__ float fast_exp2(float x) { return __builtin_amdgcn_exp2f(x); }
; __global__ void __launch_bounds__(512, 2) fwd_megakernel(Params P) {
;     ...
;         PHASE_BEGIN
;             const float lam_init = (l == 0) ? 0.2f : 0.35550907f;
;             float d1 = 0.f, d2 = 0.f;
;             { const float* a1 = P.in[I_LQ1] + l * 64; const float* b1 = P.in[I_LK1] + l * 64; const float* a2 = P.in[I_LQ2] + l * 64; const float* b2 = P.in[I_LK2] + l * 64;
;               d1 = wave_sum(a1[lane] * b1[lane]); d2 = wave_sum(a2[lane] * b2[lane]); }
;             const float lam = fast_exp2(d1 * LOG2E) - fast_exp2(d2 * LOG2E) + lam_init;
;     ...
;                 diff_unit(P, l, bh >> 2, bh & 3, s, lam, lam_init, lds, rep > 0); diff_unit(P, l, bh >> 2, bh & 3, 15 - s, lam, lam_init, lds, rep > 0); }
;         PHASE_END
;     ...
;         PHASE_BEGIN
;     ...
;             fox_unit(P, bh >> 3, bh & 7, s, lds, rep > 0); fox_unit(P, bh >> 3, bh & 7, 7 - s, lds, rep > 0); }
.LBB0_383:
	v_readfirstlane_b32 s2, v180
	s_nop 3
	s_cmp_ge_u32 s2, 0x100
	s_cbranch_scc0 .Lprio_att
	s_setprio 1
